# S4 compaction: nine page-table entries per thread prefetched up front and the first nine trips unrolled (one load latency instead of one per trip)
# speedup vs baseline: 1.0984x; 1.0052x over previous
; __device__ __forceinline__ void sdsa2_phase(const Grp& g, LAS unsigned char* shm, int G, int tid) {
;     ...
;         for (int i = tid; i < nv; i += MK_THREADS) { const float x = sc[i]; if (x > tau || (x == tau && i <= idxt)) { const unsigned slot = __hip_atomic_fetch_add(&misc[0], 1u, __ATOMIC_RELAXED, __HIP_MEMORY_SCOPE_WORKGROUP);
;             if (slot < (unsigned)TOPK) sel[slot] = i < PAST ? g.page_table[db * NPAGES + i / PAGE] * PAGE + (i % PAGE) : (0x40000000 | (i - PAST)); } }
.LBB0_1196:
	s_or_b64 exec, exec, s[52:53]
	s_and_saveexec_b64 s[52:53], s[50:51]
	s_cbranch_execz .LBB0_1210
	s_lshl_b32 s3, s2, 6
	s_mov_b64 s[50:51], 0
	v_mov_b32_e32 v22, v120
	v_mov_b32_e32 v23, v102
	v_readlane_b32 s70, v249, 28
	v_readlane_b32 s71, v249, 29
	v_lshrrev_b32_e32 v180, 7, v102
	v_add_u32_e32 v180, s3, v180
	v_ashrrev_i32_e32 v181, 31, v180
	s_nop 1
	v_lshl_add_u64 v[180:181], v[180:181], 2, s[70:71]
	global_load_dword v182, v[180:181], off
	global_load_dword v183, v[180:181], off offset:16
	global_load_dword v184, v[180:181], off offset:32
	global_load_dword v185, v[180:181], off offset:48
	global_load_dword v186, v[180:181], off offset:64
	global_load_dword v187, v[180:181], off offset:80
	global_load_dword v188, v[180:181], off offset:96
	global_load_dword v189, v[180:181], off offset:112
	global_load_dword v190, v[180:181], off offset:128
.Lc1200_0:
	ds_read_b32 v24, v22
	s_waitcnt lgkmcnt(0)
	v_cmp_gt_f32_e64 s[54:55], v24, v30
	v_cmp_ngt_f32_e32 vcc, v24, v30
	s_and_saveexec_b64 s[56:57], vcc
	v_cmp_eq_f32_e32 vcc, v24, v30
	v_cmp_le_i32_e64 s[0:1], v23, v29
	s_and_b64 s[0:1], vcc, s[0:1]
	s_andn2_b64 s[54:55], s[54:55], exec
	s_and_b64 s[0:1], s[0:1], exec
	s_or_b64 s[54:55], s[54:55], s[0:1]
	s_or_b64 exec, exec, s[56:57]
	s_and_saveexec_b64 s[0:1], s[54:55]
	s_cbranch_execz .Lc1199_0
	s_mov_b64 s[56:57], exec
	v_mbcnt_lo_u32_b32 v24, s56, 0
	v_mbcnt_hi_u32_b32 v24, s57, v24
	v_cmp_eq_u32_e32 vcc, 0, v24
	s_and_saveexec_b64 s[54:55], vcc
	s_bcnt1_i32_b64 s9, s[56:57]
	v_mov_b32_e32 v25, s9
	ds_add_rtn_u32 v25, v215, v25 offset:44288
	s_or_b64 exec, exec, s[54:55]
	s_waitcnt lgkmcnt(0)
	v_readfirstlane_b32 s9, v25
	s_nop 1
	v_add_u32_e32 v24, s9, v24
	s_movk_i32 s9, 0x100
	v_cmp_gt_u32_e32 vcc, s9, v24
	s_and_b64 exec, exec, vcc
	s_cbranch_execz .Lc1199_0
	s_movk_i32 s9, 0x1fff
	v_cmp_lt_i32_e32 vcc, s9, v23
	s_and_saveexec_b64 s[54:55], vcc
	s_xor_b64 s[54:55], exec, s[54:55]
	v_add_u32_e32 v25, 0xffffe000, v23
	v_or_b32_e32 v25, 2.0, v25
	s_andn2_saveexec_b64 s[54:55], s[54:55]
	s_cbranch_execz .Lc1198_0
	v_ashrrev_i32_e32 v25, 31, v23
	v_lshrrev_b32_e32 v25, 25, v25
	v_add_u32_e32 v25, v23, v25
	v_ashrrev_i32_e32 v26, 7, v25
	v_add_u32_e32 v26, s3, v26
	v_readlane_b32 s68, v249, 26
	v_ashrrev_i32_e32 v27, 31, v26
	v_readlane_b32 s70, v249, 28
	v_readlane_b32 s71, v249, 29
	v_readlane_b32 s69, v249, 27
	v_and_b32_e32 v25, 0xffffff80, v25
	v_readlane_b32 s68, v250, 12
	v_readlane_b32 s69, v250, 13
	v_readlane_b32 s72, v249, 30
	v_readlane_b32 s73, v249, 31
	v_readlane_b32 s74, v249, 32
	v_readlane_b32 s75, v249, 33
	v_readlane_b32 s76, v249, 34
	v_readlane_b32 s77, v249, 35
	v_readlane_b32 s78, v249, 36
	v_readlane_b32 s79, v249, 37
	v_readlane_b32 s80, v249, 38
	v_readlane_b32 s81, v249, 39
	v_readlane_b32 s82, v249, 40
	v_readlane_b32 s83, v249, 41
	s_waitcnt vmcnt(8)
	v_mov_b32_e32 v26, v182
	v_lshlrev_b32_e32 v26, 7, v26
	v_sub_u32_e32 v25, v26, v25
	v_add_u32_e32 v25, v23, v25

; __device__ __forceinline__ void sdsa2_phase(const Grp& g, LAS unsigned char* shm, int G, int tid) {
;     ...
;         for (int i = tid; i < nv; i += MK_THREADS) { const float x = sc[i]; if (x > tau || (x == tau && i <= idxt)) { const unsigned slot = __hip_atomic_fetch_add(&misc[0], 1u, __ATOMIC_RELAXED, __HIP_MEMORY_SCOPE_WORKGROUP);
;             if (slot < (unsigned)TOPK) sel[slot] = i < PAST ? g.page_table[db * NPAGES + i / PAGE] * PAGE + (i % PAGE) : (0x40000000 | (i - PAST)); } }
.Lc1200_1:
	ds_read_b32 v24, v22
	s_waitcnt lgkmcnt(0)
	v_cmp_gt_f32_e64 s[54:55], v24, v30
	v_cmp_ngt_f32_e32 vcc, v24, v30
	s_and_saveexec_b64 s[56:57], vcc
	v_cmp_eq_f32_e32 vcc, v24, v30
	v_cmp_le_i32_e64 s[0:1], v23, v29
	s_and_b64 s[0:1], vcc, s[0:1]
	s_andn2_b64 s[54:55], s[54:55], exec
	s_and_b64 s[0:1], s[0:1], exec
	s_or_b64 s[54:55], s[54:55], s[0:1]
	s_or_b64 exec, exec, s[56:57]
	s_and_saveexec_b64 s[0:1], s[54:55]
	s_cbranch_execz .Lc1199_1
	s_mov_b64 s[56:57], exec
	v_mbcnt_lo_u32_b32 v24, s56, 0
	v_mbcnt_hi_u32_b32 v24, s57, v24
	v_cmp_eq_u32_e32 vcc, 0, v24
	s_and_saveexec_b64 s[54:55], vcc
	s_bcnt1_i32_b64 s9, s[56:57]
	v_mov_b32_e32 v25, s9
	ds_add_rtn_u32 v25, v215, v25 offset:44288
	s_or_b64 exec, exec, s[54:55]
	s_waitcnt lgkmcnt(0)
	v_readfirstlane_b32 s9, v25
	s_nop 1
	v_add_u32_e32 v24, s9, v24
	s_movk_i32 s9, 0x100
	v_cmp_gt_u32_e32 vcc, s9, v24
	s_and_b64 exec, exec, vcc
	s_cbranch_execz .Lc1199_1
	s_movk_i32 s9, 0x1fff
	v_cmp_lt_i32_e32 vcc, s9, v23
	s_and_saveexec_b64 s[54:55], vcc
	s_xor_b64 s[54:55], exec, s[54:55]
	v_add_u32_e32 v25, 0xffffe000, v23
	v_or_b32_e32 v25, 2.0, v25
	s_andn2_saveexec_b64 s[54:55], s[54:55]
	s_cbranch_execz .Lc1198_1
	v_ashrrev_i32_e32 v25, 31, v23
	v_lshrrev_b32_e32 v25, 25, v25
	v_add_u32_e32 v25, v23, v25
	v_ashrrev_i32_e32 v26, 7, v25
	v_add_u32_e32 v26, s3, v26
	v_readlane_b32 s68, v249, 26
	v_ashrrev_i32_e32 v27, 31, v26
	v_readlane_b32 s70, v249, 28
	v_readlane_b32 s71, v249, 29
	v_readlane_b32 s69, v249, 27
	v_and_b32_e32 v25, 0xffffff80, v25
	v_readlane_b32 s68, v250, 12
	v_readlane_b32 s69, v250, 13
	v_readlane_b32 s72, v249, 30
	v_readlane_b32 s73, v249, 31
	v_readlane_b32 s74, v249, 32
	v_readlane_b32 s75, v249, 33
	v_readlane_b32 s76, v249, 34
	v_readlane_b32 s77, v249, 35
	v_readlane_b32 s78, v249, 36
	v_readlane_b32 s79, v249, 37
	v_readlane_b32 s80, v249, 38
	v_readlane_b32 s81, v249, 39
	v_readlane_b32 s82, v249, 40
	v_readlane_b32 s83, v249, 41
	s_waitcnt vmcnt(7)
	v_mov_b32_e32 v26, v183
	v_lshlrev_b32_e32 v26, 7, v26
	v_sub_u32_e32 v25, v26, v25
	v_add_u32_e32 v25, v23, v25

; __device__ __forceinline__ void sdsa2_phase(const Grp& g, LAS unsigned char* shm, int G, int tid) {
;     ...
;         for (int i = tid; i < nv; i += MK_THREADS) { const float x = sc[i]; if (x > tau || (x == tau && i <= idxt)) { const unsigned slot = __hip_atomic_fetch_add(&misc[0], 1u, __ATOMIC_RELAXED, __HIP_MEMORY_SCOPE_WORKGROUP);
;             if (slot < (unsigned)TOPK) sel[slot] = i < PAST ? g.page_table[db * NPAGES + i / PAGE] * PAGE + (i % PAGE) : (0x40000000 | (i - PAST)); } }
.Lc1200_2:
	ds_read_b32 v24, v22
	s_waitcnt lgkmcnt(0)
	v_cmp_gt_f32_e64 s[54:55], v24, v30
	v_cmp_ngt_f32_e32 vcc, v24, v30
	s_and_saveexec_b64 s[56:57], vcc
	v_cmp_eq_f32_e32 vcc, v24, v30
	v_cmp_le_i32_e64 s[0:1], v23, v29
	s_and_b64 s[0:1], vcc, s[0:1]
	s_andn2_b64 s[54:55], s[54:55], exec
	s_and_b64 s[0:1], s[0:1], exec
	s_or_b64 s[54:55], s[54:55], s[0:1]
	s_or_b64 exec, exec, s[56:57]
	s_and_saveexec_b64 s[0:1], s[54:55]
	s_cbranch_execz .Lc1199_2
	s_mov_b64 s[56:57], exec
	v_mbcnt_lo_u32_b32 v24, s56, 0
	v_mbcnt_hi_u32_b32 v24, s57, v24
	v_cmp_eq_u32_e32 vcc, 0, v24
	s_and_saveexec_b64 s[54:55], vcc
	s_bcnt1_i32_b64 s9, s[56:57]
	v_mov_b32_e32 v25, s9
	ds_add_rtn_u32 v25, v215, v25 offset:44288
	s_or_b64 exec, exec, s[54:55]
	s_waitcnt lgkmcnt(0)
	v_readfirstlane_b32 s9, v25
	s_nop 1
	v_add_u32_e32 v24, s9, v24
	s_movk_i32 s9, 0x100
	v_cmp_gt_u32_e32 vcc, s9, v24
	s_and_b64 exec, exec, vcc
	s_cbranch_execz .Lc1199_2
	s_movk_i32 s9, 0x1fff
	v_cmp_lt_i32_e32 vcc, s9, v23
	s_and_saveexec_b64 s[54:55], vcc
	s_xor_b64 s[54:55], exec, s[54:55]
	v_add_u32_e32 v25, 0xffffe000, v23
	v_or_b32_e32 v25, 2.0, v25
	s_andn2_saveexec_b64 s[54:55], s[54:55]
	s_cbranch_execz .Lc1198_2
	v_ashrrev_i32_e32 v25, 31, v23
	v_lshrrev_b32_e32 v25, 25, v25
	v_add_u32_e32 v25, v23, v25
	v_ashrrev_i32_e32 v26, 7, v25
	v_add_u32_e32 v26, s3, v26
	v_readlane_b32 s68, v249, 26
	v_ashrrev_i32_e32 v27, 31, v26
	v_readlane_b32 s70, v249, 28
	v_readlane_b32 s71, v249, 29
	v_readlane_b32 s69, v249, 27
	v_and_b32_e32 v25, 0xffffff80, v25
	v_readlane_b32 s68, v250, 12
	v_readlane_b32 s69, v250, 13
	v_readlane_b32 s72, v249, 30
	v_readlane_b32 s73, v249, 31
	v_readlane_b32 s74, v249, 32
	v_readlane_b32 s75, v249, 33
	v_readlane_b32 s76, v249, 34
	v_readlane_b32 s77, v249, 35
	v_readlane_b32 s78, v249, 36
	v_readlane_b32 s79, v249, 37
	v_readlane_b32 s80, v249, 38
	v_readlane_b32 s81, v249, 39
	v_readlane_b32 s82, v249, 40
	v_readlane_b32 s83, v249, 41
	s_waitcnt vmcnt(6)
	v_mov_b32_e32 v26, v184
	v_lshlrev_b32_e32 v26, 7, v26
	v_sub_u32_e32 v25, v26, v25
	v_add_u32_e32 v25, v23, v25

; __device__ __forceinline__ void sdsa2_phase(const Grp& g, LAS unsigned char* shm, int G, int tid) {
;     ...
;         for (int i = tid; i < nv; i += MK_THREADS) { const float x = sc[i]; if (x > tau || (x == tau && i <= idxt)) { const unsigned slot = __hip_atomic_fetch_add(&misc[0], 1u, __ATOMIC_RELAXED, __HIP_MEMORY_SCOPE_WORKGROUP);
;             if (slot < (unsigned)TOPK) sel[slot] = i < PAST ? g.page_table[db * NPAGES + i / PAGE] * PAGE + (i % PAGE) : (0x40000000 | (i - PAST)); } }
.Lc1200_3:
	ds_read_b32 v24, v22
	s_waitcnt lgkmcnt(0)
	v_cmp_gt_f32_e64 s[54:55], v24, v30
	v_cmp_ngt_f32_e32 vcc, v24, v30
	s_and_saveexec_b64 s[56:57], vcc
	v_cmp_eq_f32_e32 vcc, v24, v30
	v_cmp_le_i32_e64 s[0:1], v23, v29
	s_and_b64 s[0:1], vcc, s[0:1]
	s_andn2_b64 s[54:55], s[54:55], exec
	s_and_b64 s[0:1], s[0:1], exec
	s_or_b64 s[54:55], s[54:55], s[0:1]
	s_or_b64 exec, exec, s[56:57]
	s_and_saveexec_b64 s[0:1], s[54:55]
	s_cbranch_execz .Lc1199_3
	s_mov_b64 s[56:57], exec
	v_mbcnt_lo_u32_b32 v24, s56, 0
	v_mbcnt_hi_u32_b32 v24, s57, v24
	v_cmp_eq_u32_e32 vcc, 0, v24
	s_and_saveexec_b64 s[54:55], vcc
	s_bcnt1_i32_b64 s9, s[56:57]
	v_mov_b32_e32 v25, s9
	ds_add_rtn_u32 v25, v215, v25 offset:44288
	s_or_b64 exec, exec, s[54:55]
	s_waitcnt lgkmcnt(0)
	v_readfirstlane_b32 s9, v25
	s_nop 1
	v_add_u32_e32 v24, s9, v24
	s_movk_i32 s9, 0x100
	v_cmp_gt_u32_e32 vcc, s9, v24
	s_and_b64 exec, exec, vcc
	s_cbranch_execz .Lc1199_3
	s_movk_i32 s9, 0x1fff
	v_cmp_lt_i32_e32 vcc, s9, v23
	s_and_saveexec_b64 s[54:55], vcc
	s_xor_b64 s[54:55], exec, s[54:55]
	v_add_u32_e32 v25, 0xffffe000, v23
	v_or_b32_e32 v25, 2.0, v25
	s_andn2_saveexec_b64 s[54:55], s[54:55]
	s_cbranch_execz .Lc1198_3
	v_ashrrev_i32_e32 v25, 31, v23
	v_lshrrev_b32_e32 v25, 25, v25
	v_add_u32_e32 v25, v23, v25
	v_ashrrev_i32_e32 v26, 7, v25
	v_add_u32_e32 v26, s3, v26
	v_readlane_b32 s68, v249, 26
	v_ashrrev_i32_e32 v27, 31, v26
	v_readlane_b32 s70, v249, 28
	v_readlane_b32 s71, v249, 29
	v_readlane_b32 s69, v249, 27
	v_and_b32_e32 v25, 0xffffff80, v25
	v_readlane_b32 s68, v250, 12
	v_readlane_b32 s69, v250, 13
	v_readlane_b32 s72, v249, 30
	v_readlane_b32 s73, v249, 31
	v_readlane_b32 s74, v249, 32
	v_readlane_b32 s75, v249, 33
	v_readlane_b32 s76, v249, 34
	v_readlane_b32 s77, v249, 35
	v_readlane_b32 s78, v249, 36
	v_readlane_b32 s79, v249, 37
	v_readlane_b32 s80, v249, 38
	v_readlane_b32 s81, v249, 39
	v_readlane_b32 s82, v249, 40
	v_readlane_b32 s83, v249, 41
	s_waitcnt vmcnt(5)
	v_mov_b32_e32 v26, v185
	v_lshlrev_b32_e32 v26, 7, v26
	v_sub_u32_e32 v25, v26, v25
	v_add_u32_e32 v25, v23, v25

; __device__ __forceinline__ void sdsa2_phase(const Grp& g, LAS unsigned char* shm, int G, int tid) {
;     ...
;         for (int i = tid; i < nv; i += MK_THREADS) { const float x = sc[i]; if (x > tau || (x == tau && i <= idxt)) { const unsigned slot = __hip_atomic_fetch_add(&misc[0], 1u, __ATOMIC_RELAXED, __HIP_MEMORY_SCOPE_WORKGROUP);
;             if (slot < (unsigned)TOPK) sel[slot] = i < PAST ? g.page_table[db * NPAGES + i / PAGE] * PAGE + (i % PAGE) : (0x40000000 | (i - PAST)); } }
.Lc1200_4:
	ds_read_b32 v24, v22
	s_waitcnt lgkmcnt(0)
	v_cmp_gt_f32_e64 s[54:55], v24, v30
	v_cmp_ngt_f32_e32 vcc, v24, v30
	s_and_saveexec_b64 s[56:57], vcc
	v_cmp_eq_f32_e32 vcc, v24, v30
	v_cmp_le_i32_e64 s[0:1], v23, v29
	s_and_b64 s[0:1], vcc, s[0:1]
	s_andn2_b64 s[54:55], s[54:55], exec
	s_and_b64 s[0:1], s[0:1], exec
	s_or_b64 s[54:55], s[54:55], s[0:1]
	s_or_b64 exec, exec, s[56:57]
	s_and_saveexec_b64 s[0:1], s[54:55]
	s_cbranch_execz .Lc1199_4
	s_mov_b64 s[56:57], exec
	v_mbcnt_lo_u32_b32 v24, s56, 0
	v_mbcnt_hi_u32_b32 v24, s57, v24
	v_cmp_eq_u32_e32 vcc, 0, v24
	s_and_saveexec_b64 s[54:55], vcc
	s_bcnt1_i32_b64 s9, s[56:57]
	v_mov_b32_e32 v25, s9
	ds_add_rtn_u32 v25, v215, v25 offset:44288
	s_or_b64 exec, exec, s[54:55]
	s_waitcnt lgkmcnt(0)
	v_readfirstlane_b32 s9, v25
	s_nop 1
	v_add_u32_e32 v24, s9, v24
	s_movk_i32 s9, 0x100
	v_cmp_gt_u32_e32 vcc, s9, v24
	s_and_b64 exec, exec, vcc
	s_cbranch_execz .Lc1199_4
	s_movk_i32 s9, 0x1fff
	v_cmp_lt_i32_e32 vcc, s9, v23
	s_and_saveexec_b64 s[54:55], vcc
	s_xor_b64 s[54:55], exec, s[54:55]
	v_add_u32_e32 v25, 0xffffe000, v23
	v_or_b32_e32 v25, 2.0, v25
	s_andn2_saveexec_b64 s[54:55], s[54:55]
	s_cbranch_execz .Lc1198_4
	v_ashrrev_i32_e32 v25, 31, v23
	v_lshrrev_b32_e32 v25, 25, v25
	v_add_u32_e32 v25, v23, v25
	v_ashrrev_i32_e32 v26, 7, v25
	v_add_u32_e32 v26, s3, v26
	v_readlane_b32 s68, v249, 26
	v_ashrrev_i32_e32 v27, 31, v26
	v_readlane_b32 s70, v249, 28
	v_readlane_b32 s71, v249, 29
	v_readlane_b32 s69, v249, 27
	v_and_b32_e32 v25, 0xffffff80, v25
	v_readlane_b32 s68, v250, 12
	v_readlane_b32 s69, v250, 13
	v_readlane_b32 s72, v249, 30
	v_readlane_b32 s73, v249, 31
	v_readlane_b32 s74, v249, 32
	v_readlane_b32 s75, v249, 33
	v_readlane_b32 s76, v249, 34
	v_readlane_b32 s77, v249, 35
	v_readlane_b32 s78, v249, 36
	v_readlane_b32 s79, v249, 37
	v_readlane_b32 s80, v249, 38
	v_readlane_b32 s81, v249, 39
	v_readlane_b32 s82, v249, 40
	v_readlane_b32 s83, v249, 41
	s_waitcnt vmcnt(4)
	v_mov_b32_e32 v26, v186
	v_lshlrev_b32_e32 v26, 7, v26
	v_sub_u32_e32 v25, v26, v25
	v_add_u32_e32 v25, v23, v25

; __device__ __forceinline__ void sdsa2_phase(const Grp& g, LAS unsigned char* shm, int G, int tid) {
;     ...
;         for (int i = tid; i < nv; i += MK_THREADS) { const float x = sc[i]; if (x > tau || (x == tau && i <= idxt)) { const unsigned slot = __hip_atomic_fetch_add(&misc[0], 1u, __ATOMIC_RELAXED, __HIP_MEMORY_SCOPE_WORKGROUP);
;             if (slot < (unsigned)TOPK) sel[slot] = i < PAST ? g.page_table[db * NPAGES + i / PAGE] * PAGE + (i % PAGE) : (0x40000000 | (i - PAST)); } }
.Lc1200_5:
	ds_read_b32 v24, v22
	s_waitcnt lgkmcnt(0)
	v_cmp_gt_f32_e64 s[54:55], v24, v30
	v_cmp_ngt_f32_e32 vcc, v24, v30
	s_and_saveexec_b64 s[56:57], vcc
	v_cmp_eq_f32_e32 vcc, v24, v30
	v_cmp_le_i32_e64 s[0:1], v23, v29
	s_and_b64 s[0:1], vcc, s[0:1]
	s_andn2_b64 s[54:55], s[54:55], exec
	s_and_b64 s[0:1], s[0:1], exec
	s_or_b64 s[54:55], s[54:55], s[0:1]
	s_or_b64 exec, exec, s[56:57]
	s_and_saveexec_b64 s[0:1], s[54:55]
	s_cbranch_execz .Lc1199_5
	s_mov_b64 s[56:57], exec
	v_mbcnt_lo_u32_b32 v24, s56, 0
	v_mbcnt_hi_u32_b32 v24, s57, v24
	v_cmp_eq_u32_e32 vcc, 0, v24
	s_and_saveexec_b64 s[54:55], vcc
	s_bcnt1_i32_b64 s9, s[56:57]
	v_mov_b32_e32 v25, s9
	ds_add_rtn_u32 v25, v215, v25 offset:44288
	s_or_b64 exec, exec, s[54:55]
	s_waitcnt lgkmcnt(0)
	v_readfirstlane_b32 s9, v25
	s_nop 1
	v_add_u32_e32 v24, s9, v24
	s_movk_i32 s9, 0x100
	v_cmp_gt_u32_e32 vcc, s9, v24
	s_and_b64 exec, exec, vcc
	s_cbranch_execz .Lc1199_5
	s_movk_i32 s9, 0x1fff
	v_cmp_lt_i32_e32 vcc, s9, v23
	s_and_saveexec_b64 s[54:55], vcc
	s_xor_b64 s[54:55], exec, s[54:55]
	v_add_u32_e32 v25, 0xffffe000, v23
	v_or_b32_e32 v25, 2.0, v25
	s_andn2_saveexec_b64 s[54:55], s[54:55]
	s_cbranch_execz .Lc1198_5
	v_ashrrev_i32_e32 v25, 31, v23
	v_lshrrev_b32_e32 v25, 25, v25
	v_add_u32_e32 v25, v23, v25
	v_ashrrev_i32_e32 v26, 7, v25
	v_add_u32_e32 v26, s3, v26
	v_readlane_b32 s68, v249, 26
	v_ashrrev_i32_e32 v27, 31, v26
	v_readlane_b32 s70, v249, 28
	v_readlane_b32 s71, v249, 29
	v_readlane_b32 s69, v249, 27
	v_and_b32_e32 v25, 0xffffff80, v25
	v_readlane_b32 s68, v250, 12
	v_readlane_b32 s69, v250, 13
	v_readlane_b32 s72, v249, 30
	v_readlane_b32 s73, v249, 31
	v_readlane_b32 s74, v249, 32
	v_readlane_b32 s75, v249, 33
	v_readlane_b32 s76, v249, 34
	v_readlane_b32 s77, v249, 35
	v_readlane_b32 s78, v249, 36
	v_readlane_b32 s79, v249, 37
	v_readlane_b32 s80, v249, 38
	v_readlane_b32 s81, v249, 39
	v_readlane_b32 s82, v249, 40
	v_readlane_b32 s83, v249, 41
	s_waitcnt vmcnt(3)
	v_mov_b32_e32 v26, v187
	v_lshlrev_b32_e32 v26, 7, v26
	v_sub_u32_e32 v25, v26, v25
	v_add_u32_e32 v25, v23, v25

; __device__ __forceinline__ void sdsa2_phase(const Grp& g, LAS unsigned char* shm, int G, int tid) {
;     ...
;         for (int i = tid; i < nv; i += MK_THREADS) { const float x = sc[i]; if (x > tau || (x == tau && i <= idxt)) { const unsigned slot = __hip_atomic_fetch_add(&misc[0], 1u, __ATOMIC_RELAXED, __HIP_MEMORY_SCOPE_WORKGROUP);
;             if (slot < (unsigned)TOPK) sel[slot] = i < PAST ? g.page_table[db * NPAGES + i / PAGE] * PAGE + (i % PAGE) : (0x40000000 | (i - PAST)); } }
.Lc1200_6:
	ds_read_b32 v24, v22
	s_waitcnt lgkmcnt(0)
	v_cmp_gt_f32_e64 s[54:55], v24, v30
	v_cmp_ngt_f32_e32 vcc, v24, v30
	s_and_saveexec_b64 s[56:57], vcc
	v_cmp_eq_f32_e32 vcc, v24, v30
	v_cmp_le_i32_e64 s[0:1], v23, v29
	s_and_b64 s[0:1], vcc, s[0:1]
	s_andn2_b64 s[54:55], s[54:55], exec
	s_and_b64 s[0:1], s[0:1], exec
	s_or_b64 s[54:55], s[54:55], s[0:1]
	s_or_b64 exec, exec, s[56:57]
	s_and_saveexec_b64 s[0:1], s[54:55]
	s_cbranch_execz .Lc1199_6
	s_mov_b64 s[56:57], exec
	v_mbcnt_lo_u32_b32 v24, s56, 0
	v_mbcnt_hi_u32_b32 v24, s57, v24
	v_cmp_eq_u32_e32 vcc, 0, v24
	s_and_saveexec_b64 s[54:55], vcc
	s_bcnt1_i32_b64 s9, s[56:57]
	v_mov_b32_e32 v25, s9
	ds_add_rtn_u32 v25, v215, v25 offset:44288
	s_or_b64 exec, exec, s[54:55]
	s_waitcnt lgkmcnt(0)
	v_readfirstlane_b32 s9, v25
	s_nop 1
	v_add_u32_e32 v24, s9, v24
	s_movk_i32 s9, 0x100
	v_cmp_gt_u32_e32 vcc, s9, v24
	s_and_b64 exec, exec, vcc
	s_cbranch_execz .Lc1199_6
	s_movk_i32 s9, 0x1fff
	v_cmp_lt_i32_e32 vcc, s9, v23
	s_and_saveexec_b64 s[54:55], vcc
	s_xor_b64 s[54:55], exec, s[54:55]
	v_add_u32_e32 v25, 0xffffe000, v23
	v_or_b32_e32 v25, 2.0, v25
	s_andn2_saveexec_b64 s[54:55], s[54:55]
	s_cbranch_execz .Lc1198_6
	v_ashrrev_i32_e32 v25, 31, v23
	v_lshrrev_b32_e32 v25, 25, v25
	v_add_u32_e32 v25, v23, v25
	v_ashrrev_i32_e32 v26, 7, v25
	v_add_u32_e32 v26, s3, v26
	v_readlane_b32 s68, v249, 26
	v_ashrrev_i32_e32 v27, 31, v26
	v_readlane_b32 s70, v249, 28
	v_readlane_b32 s71, v249, 29
	v_readlane_b32 s69, v249, 27
	v_and_b32_e32 v25, 0xffffff80, v25
	v_readlane_b32 s68, v250, 12
	v_readlane_b32 s69, v250, 13
	v_readlane_b32 s72, v249, 30
	v_readlane_b32 s73, v249, 31
	v_readlane_b32 s74, v249, 32
	v_readlane_b32 s75, v249, 33
	v_readlane_b32 s76, v249, 34
	v_readlane_b32 s77, v249, 35
	v_readlane_b32 s78, v249, 36
	v_readlane_b32 s79, v249, 37
	v_readlane_b32 s80, v249, 38
	v_readlane_b32 s81, v249, 39
	v_readlane_b32 s82, v249, 40
	v_readlane_b32 s83, v249, 41
	s_waitcnt vmcnt(2)
	v_mov_b32_e32 v26, v188
	v_lshlrev_b32_e32 v26, 7, v26
	v_sub_u32_e32 v25, v26, v25
	v_add_u32_e32 v25, v23, v25

; __device__ __forceinline__ void sdsa2_phase(const Grp& g, LAS unsigned char* shm, int G, int tid) {
;     ...
;         for (int i = tid; i < nv; i += MK_THREADS) { const float x = sc[i]; if (x > tau || (x == tau && i <= idxt)) { const unsigned slot = __hip_atomic_fetch_add(&misc[0], 1u, __ATOMIC_RELAXED, __HIP_MEMORY_SCOPE_WORKGROUP);
;             if (slot < (unsigned)TOPK) sel[slot] = i < PAST ? g.page_table[db * NPAGES + i / PAGE] * PAGE + (i % PAGE) : (0x40000000 | (i - PAST)); } }
.Lc1200_7:
	ds_read_b32 v24, v22
	s_waitcnt lgkmcnt(0)
	v_cmp_gt_f32_e64 s[54:55], v24, v30
	v_cmp_ngt_f32_e32 vcc, v24, v30
	s_and_saveexec_b64 s[56:57], vcc
	v_cmp_eq_f32_e32 vcc, v24, v30
	v_cmp_le_i32_e64 s[0:1], v23, v29
	s_and_b64 s[0:1], vcc, s[0:1]
	s_andn2_b64 s[54:55], s[54:55], exec
	s_and_b64 s[0:1], s[0:1], exec
	s_or_b64 s[54:55], s[54:55], s[0:1]
	s_or_b64 exec, exec, s[56:57]
	s_and_saveexec_b64 s[0:1], s[54:55]
	s_cbranch_execz .Lc1199_7
	s_mov_b64 s[56:57], exec
	v_mbcnt_lo_u32_b32 v24, s56, 0
	v_mbcnt_hi_u32_b32 v24, s57, v24
	v_cmp_eq_u32_e32 vcc, 0, v24
	s_and_saveexec_b64 s[54:55], vcc
	s_bcnt1_i32_b64 s9, s[56:57]
	v_mov_b32_e32 v25, s9
	ds_add_rtn_u32 v25, v215, v25 offset:44288
	s_or_b64 exec, exec, s[54:55]
	s_waitcnt lgkmcnt(0)
	v_readfirstlane_b32 s9, v25
	s_nop 1
	v_add_u32_e32 v24, s9, v24
	s_movk_i32 s9, 0x100
	v_cmp_gt_u32_e32 vcc, s9, v24
	s_and_b64 exec, exec, vcc
	s_cbranch_execz .Lc1199_7
	s_movk_i32 s9, 0x1fff
	v_cmp_lt_i32_e32 vcc, s9, v23
	s_and_saveexec_b64 s[54:55], vcc
	s_xor_b64 s[54:55], exec, s[54:55]
	v_add_u32_e32 v25, 0xffffe000, v23
	v_or_b32_e32 v25, 2.0, v25
	s_andn2_saveexec_b64 s[54:55], s[54:55]
	s_cbranch_execz .Lc1198_7
	v_ashrrev_i32_e32 v25, 31, v23
	v_lshrrev_b32_e32 v25, 25, v25
	v_add_u32_e32 v25, v23, v25
	v_ashrrev_i32_e32 v26, 7, v25
	v_add_u32_e32 v26, s3, v26
	v_readlane_b32 s68, v249, 26
	v_ashrrev_i32_e32 v27, 31, v26
	v_readlane_b32 s70, v249, 28
	v_readlane_b32 s71, v249, 29
	v_readlane_b32 s69, v249, 27
	v_and_b32_e32 v25, 0xffffff80, v25
	v_readlane_b32 s68, v250, 12
	v_readlane_b32 s69, v250, 13
	v_readlane_b32 s72, v249, 30
	v_readlane_b32 s73, v249, 31
	v_readlane_b32 s74, v249, 32
	v_readlane_b32 s75, v249, 33
	v_readlane_b32 s76, v249, 34
	v_readlane_b32 s77, v249, 35
	v_readlane_b32 s78, v249, 36
	v_readlane_b32 s79, v249, 37
	v_readlane_b32 s80, v249, 38
	v_readlane_b32 s81, v249, 39
	v_readlane_b32 s82, v249, 40
	v_readlane_b32 s83, v249, 41
	s_waitcnt vmcnt(1)
	v_mov_b32_e32 v26, v189
	v_lshlrev_b32_e32 v26, 7, v26
	v_sub_u32_e32 v25, v26, v25
	v_add_u32_e32 v25, v23, v25

; __device__ __forceinline__ void sdsa2_phase(const Grp& g, LAS unsigned char* shm, int G, int tid) {
;     ...
;         for (int i = tid; i < nv; i += MK_THREADS) { const float x = sc[i]; if (x > tau || (x == tau && i <= idxt)) { const unsigned slot = __hip_atomic_fetch_add(&misc[0], 1u, __ATOMIC_RELAXED, __HIP_MEMORY_SCOPE_WORKGROUP);
;             if (slot < (unsigned)TOPK) sel[slot] = i < PAST ? g.page_table[db * NPAGES + i / PAGE] * PAGE + (i % PAGE) : (0x40000000 | (i - PAST)); } }
.Lc1200_8:
	ds_read_b32 v24, v22
	s_waitcnt lgkmcnt(0)
	v_cmp_gt_f32_e64 s[54:55], v24, v30
	v_cmp_ngt_f32_e32 vcc, v24, v30
	s_and_saveexec_b64 s[56:57], vcc
	v_cmp_eq_f32_e32 vcc, v24, v30
	v_cmp_le_i32_e64 s[0:1], v23, v29
	s_and_b64 s[0:1], vcc, s[0:1]
	s_andn2_b64 s[54:55], s[54:55], exec
	s_and_b64 s[0:1], s[0:1], exec
	s_or_b64 s[54:55], s[54:55], s[0:1]
	s_or_b64 exec, exec, s[56:57]
	s_and_saveexec_b64 s[0:1], s[54:55]
	s_cbranch_execz .Lc1199_8
	s_mov_b64 s[56:57], exec
	v_mbcnt_lo_u32_b32 v24, s56, 0
	v_mbcnt_hi_u32_b32 v24, s57, v24
	v_cmp_eq_u32_e32 vcc, 0, v24
	s_and_saveexec_b64 s[54:55], vcc
	s_bcnt1_i32_b64 s9, s[56:57]
	v_mov_b32_e32 v25, s9
	ds_add_rtn_u32 v25, v215, v25 offset:44288
	s_or_b64 exec, exec, s[54:55]
	s_waitcnt lgkmcnt(0)
	v_readfirstlane_b32 s9, v25
	s_nop 1
	v_add_u32_e32 v24, s9, v24
	s_movk_i32 s9, 0x100
	v_cmp_gt_u32_e32 vcc, s9, v24
	s_and_b64 exec, exec, vcc
	s_cbranch_execz .Lc1199_8
	s_movk_i32 s9, 0x1fff
	v_cmp_lt_i32_e32 vcc, s9, v23
	s_and_saveexec_b64 s[54:55], vcc
	s_xor_b64 s[54:55], exec, s[54:55]
	v_add_u32_e32 v25, 0xffffe000, v23
	v_or_b32_e32 v25, 2.0, v25
	s_andn2_saveexec_b64 s[54:55], s[54:55]
	s_cbranch_execz .Lc1198_8
	v_ashrrev_i32_e32 v25, 31, v23
	v_lshrrev_b32_e32 v25, 25, v25
	v_add_u32_e32 v25, v23, v25
	v_ashrrev_i32_e32 v26, 7, v25
	v_add_u32_e32 v26, s3, v26
	v_readlane_b32 s68, v249, 26
	v_ashrrev_i32_e32 v27, 31, v26
	v_readlane_b32 s70, v249, 28
	v_readlane_b32 s71, v249, 29
	v_readlane_b32 s69, v249, 27
	v_and_b32_e32 v25, 0xffffff80, v25
	v_readlane_b32 s68, v250, 12
	v_readlane_b32 s69, v250, 13
	v_readlane_b32 s72, v249, 30
	v_readlane_b32 s73, v249, 31
	v_readlane_b32 s74, v249, 32
	v_readlane_b32 s75, v249, 33
	v_readlane_b32 s76, v249, 34
	v_readlane_b32 s77, v249, 35
	v_readlane_b32 s78, v249, 36
	v_readlane_b32 s79, v249, 37
	v_readlane_b32 s80, v249, 38
	v_readlane_b32 s81, v249, 39
	v_readlane_b32 s82, v249, 40
	v_readlane_b32 s83, v249, 41
	s_waitcnt vmcnt(0)
	v_mov_b32_e32 v26, v190
	v_lshlrev_b32_e32 v26, 7, v26
	v_sub_u32_e32 v25, v26, v25
	v_add_u32_e32 v25, v23, v25

; __device__ __forceinline__ void sdsa2_phase(const Grp& g, LAS unsigned char* shm, int G, int tid) {
;     ...
;         for (int i = tid; i < nv; i += MK_THREADS) { const float x = sc[i]; if (x > tau || (x == tau && i <= idxt)) { const unsigned slot = __hip_atomic_fetch_add(&misc[0], 1u, __ATOMIC_RELAXED, __HIP_MEMORY_SCOPE_WORKGROUP);
.Lc1199_8:
	s_or_b64 exec, exec, s[0:1]
	v_add_u32_e32 v23, 0x200, v23
	v_cmp_lt_i32_e32 vcc, s8, v23
	s_or_b64 s[50:51], vcc, s[50:51]
	v_add_u32_e32 v22, 0x800, v22
	s_andn2_b64 exec, exec, s[50:51]
	s_cbranch_execz .LBB0_1210
	s_branch .LBB0_1200
